# first grid barrier: the 16 per-XCD arrival counters are loaded together and waited once (was 16 serial load-wait round trips)
# speedup vs baseline: 1.0081x; 1.0081x over previous
.LBB0_1147:
	v_readlane_b32 s4, v254, 13
	v_readlane_b32 s5, v254, 14
	s_mov_b64 s[6:7], -1
	s_nop 3
	global_load_dword v0, v173, s[4:5] sc1
	v_readlane_b32 s4, v254, 15
	v_readlane_b32 s5, v254, 16
	s_nop 4
	global_load_dword v1, v173, s[4:5] sc1
	v_readlane_b32 s4, v254, 17
	v_readlane_b32 s5, v254, 18
	s_nop 4
	global_load_dword v2, v173, s[4:5] sc1
	v_readlane_b32 s4, v254, 19
	v_readlane_b32 s5, v254, 20
	s_nop 4
	global_load_dword v3, v173, s[4:5] sc1
	v_readlane_b32 s4, v254, 21
	v_readlane_b32 s5, v254, 22
	s_nop 4
	global_load_dword v4, v173, s[4:5] sc1
	v_readlane_b32 s4, v254, 23
	v_readlane_b32 s5, v254, 24
	s_nop 4
	global_load_dword v5, v173, s[4:5] sc1
	v_readlane_b32 s4, v254, 25
	v_readlane_b32 s5, v254, 26
	s_nop 4
	global_load_dword v6, v173, s[4:5] sc1
	v_readlane_b32 s4, v254, 27
	v_readlane_b32 s5, v254, 28
	s_nop 4
	global_load_dword v7, v173, s[4:5] sc1
	v_readlane_b32 s4, v254, 29
	v_readlane_b32 s5, v254, 30
	s_nop 4
	global_load_dword v8, v173, s[4:5] sc1
	v_readlane_b32 s4, v254, 31
	v_readlane_b32 s5, v254, 32
	s_nop 4
	global_load_dword v9, v173, s[4:5] sc1
	v_readlane_b32 s4, v254, 33
	v_readlane_b32 s5, v254, 34
	s_nop 4
	global_load_dword v10, v173, s[4:5] sc1
	v_readlane_b32 s4, v254, 35
	v_readlane_b32 s5, v254, 36
	s_nop 4
	global_load_dword v11, v173, s[4:5] sc1
	v_readlane_b32 s4, v254, 37
	v_readlane_b32 s5, v254, 38
	s_nop 4
	global_load_dword v12, v173, s[4:5] sc1
	v_readlane_b32 s4, v254, 39
	v_readlane_b32 s5, v254, 40
	s_nop 4
	global_load_dword v13, v173, s[4:5] sc1
	v_readlane_b32 s4, v254, 41
	v_readlane_b32 s5, v254, 42
	s_nop 4
	global_load_dword v14, v173, s[4:5] sc1
	v_readlane_b32 s4, v254, 43
	v_readlane_b32 s5, v254, 44
	s_nop 4
	global_load_dword v15, v173, s[4:5] sc1
	s_mov_b64 s[4:5], -1
	s_waitcnt vmcnt(0)
	v_add_u32_e32 v16, v1, v0
	v_add_u32_e32 v16, v16, v2
	v_add_u32_e32 v16, v16, v3
	v_add_u32_e32 v16, v16, v4
	v_add_u32_e32 v16, v16, v5
	v_add_u32_e32 v16, v16, v6
	v_add_u32_e32 v16, v16, v7
	v_add_u32_e32 v16, v16, v8
	v_add_u32_e32 v16, v16, v9
	v_add_u32_e32 v16, v16, v10
	v_add_u32_e32 v16, v16, v11
	v_add_u32_e32 v16, v16, v12
	v_add_u32_e32 v16, v16, v13
	v_add_u32_e32 v16, v16, v14
	v_add_u32_e32 v16, v16, v15
	v_cmp_eq_u32_e32 vcc, s11, v16
	s_cbranch_vccnz .LBB0_1146
	s_and_b32 s4, s15, 0xff
	s_cmp_eq_u32 s4, 0
	s_mov_b64 s[4:5], -1
	s_mov_b64 s[8:9], -1
	s_sleep 1
	s_cbranch_scc0 .LBB0_1151
	v_readlane_b32 s4, v254, 11
	v_readlane_b32 s5, v254, 12
	s_nop 4
	global_load_dword v16, v173, s[4:5] sc1
	s_waitcnt vmcnt(0)
	v_cmp_eq_u32_e32 vcc, 0, v16
	s_cbranch_vccnz .LBB0_1153
	s_mov_b64 s[8:9], 0
	s_mov_b64 s[4:5], -1
